# RG-LRU scan split across both waves of each SIMD (even/odd tiles, state handed through LDS + barriers); DIR=1 SSD prefix scans interleaved
# baseline (speedup 1.0000x reference)
; __device__ __forceinline__ float log1p_small(float e) { return e < 0.03f ? e * (1.f - e * (0.5f - e * (0.33333334f - 0.25f * e))) : __logf(1.f + e); }
; template <int DIR>
; __device__ __forceinline__ void lru_item(const Params& p, int item, int lane) {
;     const int db = item & 3, blk = (item >> 2) & 7, bl = item >> 5;
;     const int r = lane & 31, h = lane >> 5;
;     const int dl = db * 32 + r, d = blk * 128 + dl;
;     const bf16_t* WGt = (const bf16_t*)(p.ws + OFF_WG);
;     const bf16_t* wa = WGt + ((size_t)((DIR * 8 + blk) * 2 + 0) * 128 + dl) * 128 + 8 * h;
;     const bf16_t* wi = WGt + ((size_t)((DIR * 8 + blk) * 2 + 1) * 128 + dl) * 128 + 8 * h;
;     bf16x8 Wa[8], Wi[8];
; #pragma unroll
;     for (int s = 0; s < 8; ++s) { Wa[s] = ld8(wa + 16 * s); Wi[s] = ld8(wi + 16 * s); }
;     bf16x8 I0, I1;
; #pragma unroll
;     for (int e = 0; e < 8; ++e) { I0[e] = (16 * (2 * db) + 8 * h + e == dl) ? (short)0x3F80 : (short)0; I1[e] = (16 * (2 * db + 1) + 8 * h + e == dl) ? (short)0x3F80 : (short)0; }
;     const float ba = p.lru_ba[DIR * 1024 + d], bi = p.lru_bi[DIR * 1024 + d];
;     const float c8 = -8.f * log1p_small(__expf(-p.lru_lambda[DIR * 1024 + d]));
;     const bf16_t* uu = (const bf16_t*)(p.ws + OFF_U);
;     bf16_t* yl = (bf16_t*)(p.ws + (DIR ? OFF_YLB : OFF_YLF));
;     float hst = 0.f;
;     auto tile_row0 = [&](int t) -> size_t { const bool cx = t < 8; const int tl = cx ? (DIR ? 7 - t : t) : (DIR ? 71 - t : t - 8);
;         return cx ? (size_t)bl * 256 + tl * 32 : (size_t)CGR + (size_t)bl * 2048 + tl * 32; };
;     bf16x8 uf[8], ui0, ui1;
;     { const bf16_t* up = uu + (tile_row0(0) + r) * 1024 + blk * 128 + 8 * h;
; #pragma unroll
;       for (int s = 0; s < 8; ++s) uf[s] = ld8(up + 16 * s);
;       ui0 = ld8(up + 32 * db); ui1 = ld8(up + 32 * db + 16); }
; __global__ void __launch_bounds__(512) mega(Params p_arg) {
;     ...
;             int l2; asm volatile("v_mbcnt_lo_u32_b32 %0, -1, 0\n\tv_mbcnt_hi_u32_b32 %0, -1, %0" : "=v"(l2));
;             int t2 = wv_ * 64 + l2;
;             const int wid2 = wv_, lane2 = t2 & 63;
;             if (wid2 < 4) for (int cu = wg; cu < BG * 8 * 2; cu += G) { const int it = (cu >> 1) * 4 + wid2; if (cu & 1) lru_item<1>(p, it, lane2); else lru_item<0>(p, it, lane2); }
.LBB0_471:
	v_readlane_b32 s2, v255, 51
	s_lshr_b32 s101, s93, 2
	s_and_b32 s93, s93, 3
	s_cmp_gt_i32 s93, 3
	v_readlane_b32 s3, v255, 52
	s_cselect_b64 s[0:1], -1, 0
	s_xor_b64 s[2:3], s[2:3], -1
	s_or_b64 s[0:1], s[0:1], s[2:3]
	v_readlane_b32 s86, v255, 9
	v_readlane_b32 s84, v255, 14
	v_readlane_b32 s72, v255, 16
	v_readlane_b32 s38, v255, 49
	v_readlane_b32 s44, v255, 47
	v_readlane_b32 s60, v255, 45
	v_readlane_b32 s24, v255, 40
	v_readlane_b32 s28, v255, 36
	s_and_b64 vcc, exec, s[0:1]
	v_readlane_b32 s88, v255, 18
	v_readlane_b32 s87, v255, 10
	v_readlane_b32 s91, v255, 11
	v_readlane_b32 s23, v255, 4
	v_readlane_b32 s85, v255, 15
	v_readlane_b32 s73, v255, 17
	s_mov_b32 s89, 0x7900000
	s_mov_b32 s63, 0x40000
	s_mov_b64 s[64:65], 0x48000
	s_mov_b32 s55, 0x50000
	s_mov_b32 s62, 0x3cf5c28f
	s_mov_b32 s56, 0x800000
	s_mov_b32 s58, 0x3f317217
	s_mov_b32 s59, 0x7f800000
	s_movk_i32 s78, 0x2a00
	v_readlane_b32 s39, v255, 50
	v_readlane_b32 s45, v255, 48
	v_readlane_b32 s61, v255, 46
	v_readlane_b32 s79, v255, 35
	v_readlane_b32 s76, v255, 44
	v_readlane_b32 s26, v255, 42
	v_readlane_b32 s25, v255, 41
	v_readlane_b32 s29, v255, 37
	v_readlane_b32 s30, v255, 38
	v_readlane_b32 s31, v255, 39
	v_mbcnt_lo_u32_b32 v0, -1, 0
	v_mbcnt_hi_u32_b32 v0, -1, v0
	v_readlane_b32 s27, v255, 43
	s_cbranch_vccnz .LBB0_497
	v_lshlrev_b32_e32 v188, 2, v0
	s_lshl_b32 s100, s93, 8
	v_add_u32_e32 v188, s100, v188
	v_add_u32_e32 v188, 0x26000, v188
	ds_write_b32 v188, v193
	v_bfe_u32 v2, v0, 5, 1
	s_lshl_b32 s0, s93, 5
	s_and_b32 s4, s0, 0x60
	v_lshlrev_b32_e32 v162, 3, v2
	v_and_b32_e32 v160, 31, v0
	v_or_b32_e32 v4, s4, v162
	v_or_b32_e32 v163, s4, v160
	v_cmp_eq_u32_e32 vcc, v162, v160
	v_mov_b32_e32 v20, 0x3f80
	v_or_b32_e32 v6, 16, v4
	v_cndmask_b32_e32 v5, 0, v20, vcc
	v_cmp_eq_u32_e32 vcc, v6, v163
	v_or_b32_e32 v8, 1, v4
	v_or_b32_e32 v7, 2, v4
	v_cndmask_b32_e32 v6, 0, v20, vcc
	v_cmp_eq_u32_e32 vcc, v8, v163
	v_or_b32_e32 v10, 17, v4
	v_or_b32_e32 v9, 18, v4
	v_cndmask_b32_e32 v8, 0, v20, vcc
	v_cmp_eq_u32_e32 vcc, v7, v163
	v_or_b32_e32 v12, 3, v4
	v_or_b32_e32 v11, 4, v4
	v_cndmask_b32_e32 v7, 0, v20, vcc
	v_cmp_eq_u32_e32 vcc, v10, v163
	v_or_b32_e32 v14, 19, v4
	v_or_b32_e32 v13, 20, v4
	v_cndmask_b32_e32 v10, 0, v20, vcc
	v_cmp_eq_u32_e32 vcc, v9, v163
	v_or_b32_e32 v16, 5, v4
	v_or_b32_e32 v15, 6, v4
	v_cndmask_b32_e32 v9, 0, v20, vcc
	v_cmp_eq_u32_e32 vcc, v12, v163
	v_or_b32_e32 v18, 21, v4
	s_add_u32 s0, s94, 0x2d80000
	v_cndmask_b32_e32 v12, 0, v20, vcc
	v_cmp_eq_u32_e32 vcc, v11, v163
	v_or_b32_e32 v17, 22, v4
	s_addc_u32 s1, s95, 0
	v_cndmask_b32_e32 v11, 0, v20, vcc
	v_cmp_eq_u32_e32 vcc, v14, v163
	v_or_b32_e32 v19, 7, v4
	v_or_b32_e32 v4, 23, v4
	v_cndmask_b32_e32 v14, 0, v20, vcc
	v_cmp_eq_u32_e32 vcc, v13, v163
	s_add_u32 s6, s94, 0x36100000
	v_and_b32_e32 v1, 63, v0
	v_cndmask_b32_e32 v13, 0, v20, vcc
	v_cmp_eq_u32_e32 vcc, v16, v163
	s_addc_u32 s7, s95, 0
	v_lshlrev_b32_e32 v192, 4, v2
	v_cndmask_b32_e32 v16, 0, v20, vcc
	v_cmp_eq_u32_e32 vcc, v15, v163
	v_lshlrev_b32_e32 v0, 8, v0
	v_lshlrev_b32_e32 v3, 7, v163
	v_cndmask_b32_e32 v15, 0, v20, vcc
	v_cmp_eq_u32_e32 vcc, v18, v163
	s_mov_b32 s2, 0x5040100
	v_lshl_add_u64 v[164:165], s[6:7], 0, v[192:193]
	v_cndmask_b32_e32 v18, 0, v20, vcc
	v_cmp_eq_u32_e32 vcc, v17, v163
	v_lshlrev_b32_e32 v2, 2, v1
	v_and_b32_e32 v192, 0x2000, v0
	v_cndmask_b32_e32 v17, 0, v20, vcc
	v_cmp_eq_u32_e32 vcc, v19, v163
	v_mov_b32_e32 v161, v193
	v_perm_b32 v50, v16, v11, s2
	v_cndmask_b32_e32 v19, 0, v20, vcc
	v_cmp_eq_u32_e32 vcc, v4, v163
	v_perm_b32 v51, v19, v15, s2
	v_perm_b32 v49, v12, v7, s2
	v_cndmask_b32_e32 v4, 0, v20, vcc
	v_perm_b32 v48, v8, v5, s2
	v_perm_b32 v55, v4, v17, s2
	v_perm_b32 v54, v18, v13, s2
	v_perm_b32 v53, v14, v9, s2
	v_perm_b32 v52, v10, v6, s2
	v_xor_b32_e32 v180, 0x80, v2
	v_cmp_gt_u32_e64 s[2:3], 32, v1
	v_lshl_add_u64 v[166:167], s[94:95], 0, v[192:193]
	s_lshl_b32 s16, s92, 1
	v_lshlrev_b32_e32 v181, 1, v3
	s_lshl_b32 s66, s4, 1
	s_mov_b32 s17, s92
	s_branch .LBB0_474
.LBB0_473:
	s_cmp_eq_u32 s101, 0
	s_cbranch_scc0 .Llru_noxa
	s_barrier

; __device__ __forceinline__ float log1p_small(float e) { return e < 0.03f ? e * (1.f - e * (0.5f - e * (0.33333334f - 0.25f * e))) : __logf(1.f + e); }
; __device__ __forceinline__ f32x16 mfma32(bf16x8 a, bf16x8 b, f32x16 c) { return __builtin_amdgcn_mfma_f32_32x32x16_bf16(a, b, c, 0, 0, 0); }
; template <int DIR>
; __device__ __forceinline__ void lru_item(const Params& p, int item, int lane) {
;     ...
;     const float c8 = -8.f * log1p_small(__expf(-p.lru_lambda[DIR * 1024 + d]));
;     const bf16_t* uu = (const bf16_t*)(p.ws + OFF_U);
;     bf16_t* yl = (bf16_t*)(p.ws + (DIR ? OFF_YLB : OFF_YLF));
;     float hst = 0.f;
;     auto tile_row0 = [&](int t) -> size_t { const bool cx = t < 8; const int tl = cx ? (DIR ? 7 - t : t) : (DIR ? 71 - t : t - 8);
;         return cx ? (size_t)bl * 256 + tl * 32 : (size_t)CGR + (size_t)bl * 2048 + tl * 32; };
;     bf16x8 uf[8], ui0, ui1;
;     { const bf16_t* up = uu + (tile_row0(0) + r) * 1024 + blk * 128 + 8 * h;
; #pragma unroll
;       for (int s = 0; s < 8; ++s) uf[s] = ld8(up + 16 * s);
;       ui0 = ld8(up + 32 * db); ui1 = ld8(up + 32 * db + 16); }
; #pragma unroll 1
;     for (int t = 0; t < 72; ++t) {
;         const bool is_ctx = t < 8;
;         const int tile = is_ctx ? (DIR ? 7 - t : t) : (DIR ? 71 - t : t - 8);
;         f32x16 Aa, Ai, Au;
; #pragma unroll
;         for (int e = 0; e < 16; ++e) { Aa[e] = 0.f; Ai[e] = 0.f; Au[e] = 0.f; }
; #pragma unroll
;         for (int s = 0; s < 8; ++s) { Aa = mfma32(uf[s], Wa[s], Aa); Ai = mfma32(uf[s], Wi[s], Ai); }
;         Au = mfma32(ui0, I0, Au); Au = mfma32(ui1, I1, Au);
;         { const int tn = t + 1 < 72 ? t + 1 : 71; const bf16_t* up = uu + (tile_row0(tn) + r) * 1024 + blk * 128 + 8 * h;
; #pragma unroll
;           for (int s = 0; s < 8; ++s) uf[s] = ld8(up + 16 * s);
;           ui0 = ld8(up + 32 * db); ui1 = ld8(up + 32 * db + 16); }
.LBB0_477:
	s_andn2_saveexec_b64 s[4:5], s[8:9]
	v_fmamk_f32 v0, v1, 0xbe800000, v237
	v_fma_f32 v0, -v1, v0, 0.5
	v_fma_f32 v0, -v1, v0, 1.0
	v_mul_f32_e32 v0, v1, v0
	s_or_b64 exec, exec, s[4:5]
	s_ashr_i32 s8, s11, 5
	s_ashr_i32 s9, s8, 31
	s_lshl_b64 s[4:5], s[8:9], 8
	v_mov_b32_e32 v3, s5
	v_or_b32_e32 v2, s4, v160
	v_lshlrev_b64 v[2:3], 11, v[2:3]
	v_lshl_add_u64 v[2:3], s[6:7], 0, v[2:3]
	s_lshl_b32 s14, s10, 1
	s_mov_b32 s15, s67
	v_lshl_add_u64 v[2:3], v[2:3], 0, s[14:15]
	v_lshl_add_u64 v[2:3], v[2:3], 0, v[192:193]
	s_lshl_b32 s12, s101, 16
	s_sub_u32 s12, 0x70000, s12
	s_mov_b32 s13, 0
	v_lshl_add_u64 v[4:5], v[2:3], 0, s[12:13]
	s_lshl_b32 s12, s101, 16
	s_sub_u32 s12, 0x70000, s12
	v_add_co_u32_e32 v2, vcc, s12, v2
	v_lshl_add_u64 v[174:175], v[164:165], 0, s[14:15]
	s_nop 0
	v_addc_co_u32_e32 v3, vcc, 0, v3, vcc
	global_load_dwordx4 v[148:151], v[4:5], off offset:32
	global_load_dwordx4 v[144:147], v[4:5], off offset:64
	global_load_dwordx4 v[140:143], v[4:5], off offset:96
	global_load_dwordx4 v[136:139], v[4:5], off offset:128
	global_load_dwordx4 v[132:135], v[4:5], off offset:160
	global_load_dwordx4 v[128:131], v[4:5], off offset:192
	global_load_dwordx4 v[156:159], v[2:3], off
	global_load_dwordx4 v[124:127], v[4:5], off offset:224
	v_lshl_add_u64 v[2:3], v[4:5], 0, s[66:67]
	global_load_dwordx4 v[152:155], v[2:3], off
	global_load_dwordx4 v[120:123], v[2:3], off offset:32
	s_lshl_b64 s[14:15], s[8:9], 11
	s_add_u32 s13, s14, 0x1000
	v_mul_f32_e32 v0, 0xc1000000, v0
	s_addc_u32 s14, s15, 0
	s_lshl_b64 s[8:9], s[8:9], 22
	v_mul_f32_e32 v176, 0x3fb8aa3b, v0
	v_mov_b32_e32 v1, s9
	v_or_b32_e32 v0, s8, v182
	s_mov_b32 s12, s101
	v_mov_b32_e32 v171, v170
	v_mov_b32_e32 v173, v172
	v_mov_b32_e32 v177, v176
	v_lshl_add_u64 v[178:179], v[166:167], 0, v[0:1]
	v_mov_b32_e32 v183, 0
	s_lshl_b32 s8, s101, 16
	s_sub_u32 s8, 0, s8
	s_subb_u32 s9, 0, 0
	s_waitcnt vmcnt(0)
	s_waitcnt lgkmcnt(0)
	s_cmp_eq_u32 s101, 0
	s_cbranch_scc1 .Llru_v1_nob
	s_barrier
.Llru_v1_nob:
	s_branch .LBB0_481
.LBB0_480:
	s_add_u32 s8, s8, 0xfffe0000
	v_cndmask_b32_e64 v0, v0, v17, s[2:3]
	v_cndmask_b32_e64 v183, v2, v19, s[2:3]
	s_addc_u32 s9, s9, -1
	s_cmpk_ge_i32 s12, 0x48
	v_fmac_f32_e32 v183, v0, v4
	ds_write_b32 v188, v183
	s_waitcnt lgkmcnt(0)
	s_barrier
	s_cbranch_scc1 .LBB0_483
.LBB0_481:
	v_mfma_f32_32x32x16_bf16 v[32:47], v[156:159], v[56:59], 0
	v_mov_b64_e32 v[186:187], v[126:127]
	v_mov_b64_e32 v[184:185], v[124:125]
	s_mov_b32 s15, s12
	s_add_i32 s12, s12, 2
	s_min_u32 s22, s12, 0x47
	s_cmp_lt_u32 s22, 8
	v_mfma_f32_32x32x16_bf16 v[32:47], v[148:151], v[64:67], v[32:47]
	s_cselect_b64 s[18:19], -1, 0
	s_and_b64 s[20:21], s[18:19], exec
	s_cselect_b32 s20, 7, 0x47
	s_sub_i32 s20, s20, s22
	s_lshl_b32 s20, s20, 5
	s_ashr_i32 s21, s20, 31
	s_and_b64 s[18:19], s[18:19], exec
	v_mfma_f32_32x32x16_bf16 v[16:31], v[156:159], v[60:63], 0
	s_cselect_b32 s19, s4, s13
	s_cselect_b32 s18, s5, s14
	s_add_u32 s19, s19, s20
	s_addc_u32 s18, s18, s21
	v_mov_b32_e32 v125, s18
	v_or_b32_e32 v124, s19, v160
	v_lshlrev_b64 v[124:125], 11, v[124:125]
	v_mfma_f32_32x32x16_bf16 v[32:47], v[144:147], v[72:75], v[32:47]
	s_cmp_lt_u32 s15, 8
	v_mfma_f32_32x32x16_bf16 v[16:31], v[148:151], v[68:71], v[16:31]
	v_mfma_f32_32x32x16_bf16 v[32:47], v[140:143], v[80:83], v[32:47]
	v_mfma_f32_32x32x16_bf16 v[16:31], v[144:147], v[76:79], v[16:31]
	v_mfma_f32_32x32x16_bf16 v[32:47], v[136:139], v[88:91], v[32:47]
	v_mfma_f32_32x32x16_bf16 v[16:31], v[140:143], v[84:87], v[16:31]
	v_mfma_f32_32x32x16_bf16 v[32:47], v[132:135], v[96:99], v[32:47]
	v_mfma_f32_32x32x16_bf16 v[16:31], v[136:139], v[92:95], v[16:31]
	v_mfma_f32_32x32x16_bf16 v[32:47], v[128:131], v[104:107], v[32:47]
	v_mfma_f32_32x32x16_bf16 v[16:31], v[132:135], v[100:103], v[16:31]
	v_mfma_f32_32x32x16_bf16 v[32:47], v[184:187], v[112:115], v[32:47]
	v_mfma_f32_32x32x16_bf16 v[16:31], v[128:131], v[108:111], v[16:31]
	s_nop 10
	v_add_f32_e64 v32, v170, v32
	v_add_f32_e64 v33, v171, v33
	v_add_f32_e64 v34, v170, v34
	v_add_f32_e64 v35, v171, v35
	v_mul_f32_e64 v32, v32, s90
	v_mul_f32_e64 v33, v33, s90
	v_pk_mul_f32 v[34:35], v[34:35], s[90:91] op_sel_hi:[1,0]
	v_exp_f32_e32 v32, v32
	v_exp_f32_e32 v33, v33
	v_exp_f32_e32 v34, v34
	v_mfma_f32_32x32x16_bf16 v[16:31], v[184:187], v[116:119], v[16:31]
	v_exp_f32_e32 v35, v35
	v_pk_add_f32 v[32:33], v[32:33], 1.0 op_sel_hi:[1,0]
	v_pk_add_f32 v[36:37], v[170:171], v[36:37]
	v_rcp_f32_e32 v32, v32
	v_rcp_f32_e32 v33, v33
	v_pk_mul_f32 v[36:37], v[36:37], s[90:91] op_sel_hi:[1,0]
	s_nop 5
	v_pk_add_f32 v[16:17], v[172:173], v[16:17]
	v_mfma_f32_32x32x16_bf16 v[0:15], v[152:155], v[48:51], 0
	v_mul_f32_e64 v16, v16, s90
	v_mul_f32_e64 v17, v17, s90
	v_exp_f32_e32 v36, v36
	v_exp_f32_e32 v184, v16
	v_exp_f32_e32 v185, v17
	v_pk_mul_f32 v[16:17], v[176:177], v[32:33]
	v_exp_f32_e32 v37, v37
	v_exp_f32_e32 v16, v16
	v_exp_f32_e32 v17, v17
	v_mfma_f32_32x32x16_bf16 v[0:15], v[120:123], v[52:55], v[0:15]
	v_add_f32_e64 v32, v184, 1.0
	v_add_f32_e64 v33, v185, 1.0
	v_lshl_add_u64 v[152:153], v[174:175], 0, v[124:125]
	v_fma_f32 v184, -v16, v16, 1.0
	v_fma_f32 v185, -v17, v17, 1.0
	v_rcp_f32_e32 v32, v32
	v_rcp_f32_e32 v33, v33
	v_max_f32_e32 v184, 0, v184
	v_max_f32_e32 v185, 0, v185
	v_sqrt_f32_e32 v184, v184
	v_sqrt_f32_e32 v185, v185
	s_nop 0
	v_pk_mul_f32 v[0:1], v[32:33], v[0:1]
	global_load_dwordx4 v[156:159], v[152:153], off
	global_load_dwordx4 v[148:151], v[152:153], off offset:32
	global_load_dwordx4 v[144:147], v[152:153], off offset:64
	global_load_dwordx4 v[140:143], v[152:153], off offset:96
	global_load_dwordx4 v[136:139], v[152:153], off offset:128
; template <int DIR>
; __device__ __forceinline__ void lru_item(const Params& p, int item, int lane) {
;     ...
;         { const int tn = t + 1 < 72 ? t + 1 : 71; const bf16_t* up = uu + (tile_row0(tn) + r) * 1024 + blk * 128 + 8 * h;
; #pragma unroll
;           for (int s = 0; s < 8; ++s) uf[s] = ld8(up + 16 * s);
;           ui0 = ld8(up + 32 * db); ui1 = ld8(up + 32 * db + 16); }
;         float av[16], bv[16];
; #pragma unroll
;         for (int e = 0; e < 16; e += 2) {
;             const f32x2 xa = (f32x2){Aa[e], Aa[e + 1]} + ba, xi = (f32x2){Ai[e], Ai[e + 1]} + bi, uv = (f32x2){Au[e], Au[e + 1]};
;             const f32x2 ta = xa * -1.4426950408889634f, ti = xi * -1.4426950408889634f;
;             f32x2 da, di; da.x = __builtin_amdgcn_exp2f(ta.x); da.y = __builtin_amdgcn_exp2f(ta.y); di.x = __builtin_amdgcn_exp2f(ti.x); di.y = __builtin_amdgcn_exp2f(ti.y);
;             da = da + 1.f; di = di + 1.f;
;             f32x2 ra, ri; ra.x = __builtin_amdgcn_rcpf(da.x); ra.y = __builtin_amdgcn_rcpf(da.y); ri.x = __builtin_amdgcn_rcpf(di.x); ri.y = __builtin_amdgcn_rcpf(di.y);
;             const f32x2 la = ra * (c8 * 1.4426950408889634f);
;             f32x2 a; a.x = __builtin_amdgcn_exp2f(la.x); a.y = __builtin_amdgcn_exp2f(la.y);
;             f32x2 om = 1.f - a * a; om.x = fmaxf(om.x, 0.f); om.y = fmaxf(om.y, 0.f);
;             f32x2 sq; sq.x = __builtin_amdgcn_sqrtf(om.x); sq.y = __builtin_amdgcn_sqrtf(om.y);
;             const f32x2 b = sq * (ri * uv);
;             const int k0 = DIR ? 15 - e : e, k1 = DIR ? 14 - e : e + 1;
;             av[k0] = a.x; bv[k0] = b.x; av[k1] = a.y; bv[k1] = b.y;
;         }
	global_load_dwordx4 v[132:135], v[152:153], off offset:160
	global_load_dwordx4 v[128:131], v[152:153], off offset:192
	global_load_dwordx4 v[124:127], v[152:153], off offset:224
	v_lshl_add_u64 v[120:121], v[152:153], 0, s[66:67]
	v_pk_mul_f32 v[32:33], v[0:1], v[184:185]
	v_pk_add_f32 v[0:1], v[172:173], v[18:19]
	v_pk_add_f32 v[18:19], v[34:35], 1.0 op_sel_hi:[1,0]
	v_pk_mul_f32 v[0:1], v[0:1], s[90:91] op_sel_hi:[1,0]
	v_rcp_f32_e32 v18, v18
	v_rcp_f32_e32 v19, v19
	v_exp_f32_e32 v34, v0
	v_exp_f32_e32 v35, v1
	global_load_dwordx4 v[152:155], v[120:121], off
	s_nop 0
	global_load_dwordx4 v[120:123], v[120:121], off offset:32
	v_pk_mul_f32 v[0:1], v[176:177], v[18:19]
	v_pk_add_f32 v[18:19], v[34:35], 1.0 op_sel_hi:[1,0]
	v_exp_f32_e32 v0, v0
	v_exp_f32_e32 v1, v1
	v_rcp_f32_e32 v18, v18
	v_rcp_f32_e32 v19, v19
	v_pk_fma_f32 v[34:35], v[0:1], v[0:1], 1.0 op_sel_hi:[1,1,0] neg_lo:[1,0,0] neg_hi:[1,0,0]
	s_nop 0
	v_max_f32_e32 v34, 0, v34
	v_max_f32_e32 v35, 0, v35
	v_pk_mul_f32 v[2:3], v[18:19], v[2:3]
	v_pk_add_f32 v[18:19], v[172:173], v[20:21]
	v_pk_add_f32 v[20:21], v[36:37], 1.0 op_sel_hi:[1,0]
	v_sqrt_f32_e32 v34, v34
	v_sqrt_f32_e32 v35, v35
	v_rcp_f32_e32 v20, v20
	v_rcp_f32_e32 v21, v21
	v_pk_mul_f32 v[18:19], v[18:19], s[90:91] op_sel_hi:[1,0]
	v_pk_mul_f32 v[2:3], v[2:3], v[34:35]
	v_exp_f32_e32 v34, v18
	v_exp_f32_e32 v35, v19
	v_pk_mul_f32 v[18:19], v[176:177], v[20:21]
	v_pk_add_f32 v[36:37], v[170:171], v[38:39]
	v_exp_f32_e32 v18, v18
	v_exp_f32_e32 v19, v19
	v_pk_add_f32 v[20:21], v[34:35], 1.0 op_sel_hi:[1,0]
	v_pk_mul_f32 v[36:37], v[36:37], s[90:91] op_sel_hi:[1,0]
	v_rcp_f32_e32 v20, v20
	v_pk_fma_f32 v[34:35], v[18:19], v[18:19], 1.0 op_sel_hi:[1,1,0] neg_lo:[1,0,0] neg_hi:[1,0,0]
	v_rcp_f32_e32 v21, v21
	v_max_f32_e32 v34, 0, v34
	v_max_f32_e32 v35, 0, v35
	v_sqrt_f32_e32 v34, v34
	v_sqrt_f32_e32 v35, v35
	v_exp_f32_e32 v36, v36
	v_exp_f32_e32 v37, v37
	v_pk_mul_f32 v[4:5], v[20:21], v[4:5]
	s_nop 0
	v_pk_mul_f32 v[20:21], v[4:5], v[34:35]
	v_pk_add_f32 v[4:5], v[172:173], v[22:23]
	v_pk_add_f32 v[22:23], v[36:37], 1.0 op_sel_hi:[1,0]
	v_pk_mul_f32 v[4:5], v[4:5], s[90:91] op_sel_hi:[1,0]
	v_rcp_f32_e32 v22, v22
	v_rcp_f32_e32 v23, v23
	v_exp_f32_e32 v34, v4
	v_exp_f32_e32 v35, v5
	v_pk_add_f32 v[36:37], v[170:171], v[40:41]
	v_pk_mul_f32 v[4:5], v[176:177], v[22:23]
	v_pk_mul_f32 v[36:37], v[36:37], s[90:91] op_sel_hi:[1,0]
	v_pk_add_f32 v[22:23], v[34:35], 1.0 op_sel_hi:[1,0]
	v_exp_f32_e32 v4, v4
	v_exp_f32_e32 v5, v5
	v_rcp_f32_e32 v22, v22
	v_rcp_f32_e32 v23, v23
	v_exp_f32_e32 v36, v36
	v_exp_f32_e32 v37, v37
	v_pk_fma_f32 v[34:35], v[4:5], v[4:5], 1.0 op_sel_hi:[1,1,0] neg_lo:[1,0,0] neg_hi:[1,0,0]
	v_pk_mul_f32 v[6:7], v[22:23], v[6:7]
	v_pk_add_f32 v[22:23], v[172:173], v[24:25]
	v_pk_add_f32 v[24:25], v[36:37], 1.0 op_sel_hi:[1,0]
	v_max_f32_e32 v34, 0, v34
	v_max_f32_e32 v35, 0, v35
	v_rcp_f32_e32 v24, v24
	v_rcp_f32_e32 v25, v25
	v_sqrt_f32_e32 v34, v34
	v_sqrt_f32_e32 v35, v35
	v_pk_mul_f32 v[22:23], v[22:23], s[90:91] op_sel_hi:[1,0]
	v_pk_mul_f32 v[24:25], v[176:177], v[24:25]
	v_exp_f32_e32 v22, v22
	v_exp_f32_e32 v23, v23
	v_pk_mul_f32 v[6:7], v[6:7], v[34:35]
	v_exp_f32_e32 v34, v24
	v_exp_f32_e32 v35, v25
	v_pk_add_f32 v[36:37], v[170:171], v[42:43]
	v_pk_add_f32 v[22:23], v[22:23], 1.0 op_sel_hi:[1,0]
	v_pk_mul_f32 v[36:37], v[36:37], s[90:91] op_sel_hi:[1,0]
	v_rcp_f32_e32 v22, v22
	v_rcp_f32_e32 v23, v23
	v_exp_f32_e32 v36, v36
	v_exp_f32_e32 v37, v37
	v_pk_fma_f32 v[24:25], v[34:35], v[34:35], 1.0 op_sel_hi:[1,1,0] neg_lo:[1,0,0] neg_hi:[1,0,0]
	v_pk_mul_f32 v[8:9], v[22:23], v[8:9]
	v_max_f32_e32 v24, 0, v24
	v_max_f32_e32 v25, 0, v25
	v_sqrt_f32_e32 v24, v24
	v_sqrt_f32_e32 v25, v25
	v_pk_add_f32 v[22:23], v[36:37], 1.0 op_sel_hi:[1,0]
	v_mov_b32_e32 v42, v6
	v_rcp_f32_e32 v22, v22
	v_rcp_f32_e32 v23, v23
	v_pk_mul_f32 v[38:39], v[8:9], v[24:25]
	v_pk_add_f32 v[8:9], v[172:173], v[26:27]
	v_pk_add_f32 v[26:27], v[170:171], v[44:45]
	v_pk_mul_f32 v[8:9], v[8:9], s[90:91] op_sel_hi:[1,0]
	v_pk_mul_f32 v[26:27], v[26:27], s[90:91] op_sel_hi:[1,0]
	v_exp_f32_e32 v24, v8
	v_exp_f32_e32 v25, v9
	v_pk_mul_f32 v[8:9], v[176:177], v[22:23]
	v_exp_f32_e32 v26, v26
	v_exp_f32_e32 v8, v8
	v_exp_f32_e32 v9, v9
	v_pk_add_f32 v[22:23], v[24:25], 1.0 op_sel_hi:[1,0]
	v_exp_f32_e32 v27, v27
	v_rcp_f32_e32 v22, v22
	v_pk_fma_f32 v[24:25], v[8:9], v[8:9], 1.0 op_sel_hi:[1,1,0] neg_lo:[1,0,0] neg_hi:[1,0,0]
	v_rcp_f32_e32 v23, v23
	v_max_f32_e32 v24, 0, v24
	v_max_f32_e32 v25, 0, v25
	v_sqrt_f32_e32 v24, v24
	v_sqrt_f32_e32 v25, v25
	v_pk_mul_f32 v[10:11], v[22:23], v[10:11]
	v_pk_add_f32 v[22:23], v[172:173], v[28:29]
	v_pk_add_f32 v[28:29], v[172:173], v[30:31]
	v_pk_mul_f32 v[10:11], v[10:11], v[24:25]
	v_pk_add_f32 v[24:25], v[26:27], 1.0 op_sel_hi:[1,0]
	v_pk_mul_f32 v[22:23], v[22:23], s[90:91] op_sel_hi:[1,0]
	v_rcp_f32_e32 v24, v24
	v_rcp_f32_e32 v25, v25
	v_exp_f32_e32 v22, v22
	v_exp_f32_e32 v23, v23
	v_pk_mul_f32 v[28:29], v[28:29], s[90:91] op_sel_hi:[1,0]
	v_pk_mul_f32 v[24:25], v[176:177], v[24:25]
	v_exp_f32_e32 v28, v28
	v_exp_f32_e32 v36, v24
	v_exp_f32_e32 v37, v25
	v_pk_add_f32 v[22:23], v[22:23], 1.0 op_sel_hi:[1,0]
	v_exp_f32_e32 v29, v29
	v_rcp_f32_e32 v24, v22
	v_rcp_f32_e32 v25, v23
	v_pk_fma_f32 v[22:23], v[36:37], v[36:37], 1.0 op_sel_hi:[1,1,0] neg_lo:[1,0,0] neg_hi:[1,0,0]
	v_pk_add_f32 v[28:29], v[28:29], 1.0 op_sel_hi:[1,0]
	v_max_f32_e32 v26, 0, v22
	v_max_f32_e32 v27, 0, v23
	v_pk_add_f32 v[22:23], v[170:171], v[46:47]
	v_sqrt_f32_e32 v26, v26
	v_pk_mul_f32 v[22:23], v[22:23], s[90:91] op_sel_hi:[1,0]
	v_sqrt_f32_e32 v27, v27
	v_exp_f32_e32 v22, v22
	v_exp_f32_e32 v23, v23
; __device__ __forceinline__ unsigned short f2bf(float f) { return (unsigned short)(cvt_pk_bf16(f, 0.f) & 0xffffu); }
; __device__ __forceinline__ float lane_get(float v, int src_lane) { return __int_as_float(__builtin_amdgcn_ds_bpermute(src_lane << 2, __float_as_int(v))); }
; template <int DIR>
; __device__ __forceinline__ void lru_item(const Params& p, int item, int lane) {
;     ...
;         const int hh = DIR ? 1 - h : h;
;         float Ag[4], Bg[4];
; #pragma unroll
;         for (int q = 0; q < 4; q += 2) {
;             f32x2 A = (f32x2){av[4 * q], av[4 * q + 4]}, B = (f32x2){bv[4 * q], bv[4 * q + 4]};
; #pragma unroll
;             for (int k = 1; k < 4; ++k) { const f32x2 ak = (f32x2){av[4 * q + k], av[4 * q + 4 + k]}, bk = (f32x2){bv[4 * q + k], bv[4 * q + 4 + k]};
;                 A = A * ak; B = B * ak + bk; av[4 * q + k] = A.x; av[4 * q + 4 + k] = A.y; bv[4 * q + k] = B.x; bv[4 * q + 4 + k] = B.y; }
;             Ag[q] = A.x; Ag[q + 1] = A.y; Bg[q] = B.x; Bg[q + 1] = B.y;
;         }
;         float Ap[4], Bp[4];
; #pragma unroll
;         for (int q = 0; q < 4; ++q) { Ap[q] = lane_get(Ag[q], lane ^ 32); Bp[q] = lane_get(Bg[q], lane ^ 32); }
;         float st = hst, hs[4];
; #pragma unroll
;         for (int Gi = 0; Gi < 8; ++Gi) {
;             const int q = Gi >> 1; const bool own = (hh == (Gi & 1));
;             const float A = own ? Ag[q] : Ap[q], B = own ? Bg[q] : Bp[q];
;             if (own) hs[q] = st;
;             st = A * st + B;
;         }
;         hst = st;
;         if (!is_ctx) {
;             bf16_t* yr = yl + ((size_t)bl * 2048 + tile * 32) * 1024 + d;
; #pragma unroll
;             for (int e = 0; e < 16; ++e) { const int k = DIR ? 15 - e : e; const float hv = av[k] * hs[k >> 2] + bv[k];
;                 const int tok = (e & 3) + 8 * (e >> 2) + 4 * h; yr[(size_t)tok * 1024] = f2bf(hv); }
	v_rcp_f32_e32 v28, v28
	v_rcp_f32_e32 v29, v29
	v_pk_mul_f32 v[12:13], v[24:25], v[12:13]
	v_pk_add_f32 v[22:23], v[22:23], 1.0 op_sel_hi:[1,0]
	v_pk_mul_f32 v[40:41], v[12:13], v[26:27]
	v_rcp_f32_e32 v22, v22
	v_rcp_f32_e32 v23, v23
	v_pk_mul_f32 v[12:13], v[28:29], v[14:15]
	v_mov_b32_e32 v15, v9
	v_mov_b32_e32 v25, v11
	v_pk_mul_f32 v[22:23], v[176:177], v[22:23]
	v_mov_b32_e32 v27, v8
	v_exp_f32_e32 v22, v22
	v_exp_f32_e32 v23, v23
	v_mov_b32_e32 v29, v10
	v_mov_b32_e32 v43, v2
	v_mov_b32_e32 v26, v22
	v_pk_fma_f32 v[30:31], v[22:23], v[22:23], 1.0 op_sel_hi:[1,1,0] neg_lo:[1,0,0] neg_hi:[1,0,0]
	v_mov_b32_e32 v14, v23
	v_max_f32_e32 v30, 0, v30
	v_max_f32_e32 v31, 0, v31
	v_sqrt_f32_e32 v30, v30
	v_sqrt_f32_e32 v31, v31
	v_pk_mul_f32 v[14:15], v[14:15], v[26:27]
	v_mov_b32_e32 v44, v21
	v_mov_b32_e32 v45, v33
	v_pk_mul_f32 v[12:13], v[12:13], v[30:31]
	v_mov_b32_e32 v30, v41
	v_mov_b32_e32 v24, v13
	v_mov_b32_e32 v28, v12
	v_pk_fma_f32 v[24:25], v[26:27], v[24:25], v[28:29]
	v_mov_b32_e32 v28, v37
	v_mov_b32_e32 v29, v35
	v_mov_b32_e32 v31, v39
	v_pk_mul_f32 v[26:27], v[28:29], v[14:15]
	v_pk_fma_f32 v[28:29], v[28:29], v[24:25], v[30:31]
	v_mov_b32_e32 v37, v34
	v_mov_b32_e32 v41, v38
	v_pk_mul_f32 v[30:31], v[36:37], v[26:27]
	v_pk_fma_f32 v[34:35], v[36:37], v[28:29], v[40:41]
	v_mov_b32_e32 v36, v5
	v_mov_b32_e32 v37, v1
	v_mov_b32_e32 v38, v7
	v_mov_b32_e32 v39, v3
	v_mov_b32_e32 v40, v4
	v_mov_b32_e32 v41, v0
	v_pk_mul_f32 v[36:37], v[36:37], v[40:41]
	v_pk_fma_f32 v[38:39], v[40:41], v[38:39], v[42:43]
	v_mov_b32_e32 v42, v19
	v_mov_b32_e32 v43, v17
	ds_bpermute_b32 v4, v180, v30
	ds_bpermute_b32 v8, v180, v34
	v_pk_mul_f32 v[40:41], v[42:43], v[36:37]
	v_pk_fma_f32 v[42:43], v[42:43], v[38:39], v[44:45]
	v_mov_b32_e32 v19, v16
	v_mov_b32_e32 v21, v32
	v_pk_mul_f32 v[16:17], v[18:19], v[40:41]
	v_pk_fma_f32 v[18:19], v[18:19], v[42:43], v[20:21]
	ds_bpermute_b32 v12, v180, v31
	ds_bpermute_b32 v20, v180, v35
	ds_bpermute_b32 v21, v180, v16
	ds_bpermute_b32 v22, v180, v18
	s_waitcnt lgkmcnt(0)
	v_cndmask_b32_e64 v10, v30, v4, s[2:3]
	v_cndmask_b32_e64 v6, v34, v8, s[2:3]
	s_barrier
	ds_read_b32 v183, v188
	s_waitcnt lgkmcnt(0)
	ds_bpermute_b32 v0, v180, v17
	ds_bpermute_b32 v2, v180, v19
	v_fmac_f32_e32 v6, v183, v10
	v_cndmask_b32_e64 v4, v4, v30, s[2:3]
	v_cndmask_b32_e64 v8, v8, v34, s[2:3]
	v_fmac_f32_e32 v8, v4, v6
	v_cndmask_b32_e64 v4, v31, v12, s[2:3]
	v_cndmask_b32_e64 v10, v35, v20, s[2:3]
	v_fmac_f32_e32 v10, v4, v8
	v_cndmask_b32_e64 v4, v12, v31, s[2:3]
	v_cndmask_b32_e64 v12, v20, v35, s[2:3]
	v_fmac_f32_e32 v12, v4, v10
	v_cndmask_b32_e64 v4, v16, v21, s[2:3]
	v_cndmask_b32_e64 v20, v18, v22, s[2:3]
	v_fmac_f32_e32 v20, v4, v12
	v_cndmask_b32_e64 v4, v21, v16, s[2:3]
	v_cndmask_b32_e64 v21, v22, v18, s[2:3]
	v_fmac_f32_e32 v21, v4, v20
	s_waitcnt lgkmcnt(1)
	v_cndmask_b32_e64 v22, v17, v0, s[2:3]
	s_waitcnt lgkmcnt(0)
	v_cndmask_b32_e64 v4, v19, v2, s[2:3]
	v_fmac_f32_e32 v4, v22, v21
	s_waitcnt vmcnt(0)
	s_cbranch_scc1 .LBB0_480
	v_cndmask_b32_e64 v22, v21, v4, s[2:3]
	v_cndmask_b32_e64 v12, v12, v20, s[2:3]
	v_lshl_add_u64 v[20:21], v[178:179], 0, s[8:9]
	s_mov_b32 s15, 0x1bd70000
	v_add_co_u32_e32 v32, vcc, s15, v20
	s_mov_b32 s15, 0x1bd71000
	s_nop 0
	v_addc_co_u32_e32 v33, vcc, 0, v21, vcc
	v_cndmask_b32_e64 v8, v8, v10, s[2:3]
	v_cndmask_b32_e64 v10, v183, v6, s[2:3]
	v_fma_f32 v6, v17, v22, v19
	v_add_co_u32_e32 v44, vcc, s15, v20
	v_cvt_pk_bf16_f32 v6, v6, v193
	s_mov_b32 s15, 0x1bd74000
	s_nop 0
	v_addc_co_u32_e32 v45, vcc, 0, v21, vcc
	global_store_short v[44:45], v6, off offset:-4096
	v_fma_f32 v6, v41, v22, v43
	v_cvt_pk_bf16_f32 v6, v6, v193
	global_store_short v[32:33], v6, off offset:2048
	v_fma_f32 v6, v37, v22, v39
	v_add_co_u32_e32 v32, vcc, s15, v20
	v_cvt_pk_bf16_f32 v6, v6, v193
	global_store_short v[44:45], v6, off
	v_fmac_f32_e32 v3, v1, v22
	v_cvt_pk_bf16_f32 v1, v3, v193
	v_addc_co_u32_e32 v33, vcc, 0, v21, vcc
	s_mov_b32 s15, 0x1bd75000
	global_store_short v[44:45], v1, off offset:2048
	v_fma_f32 v1, v16, v12, v18
	v_add_co_u32_e32 v44, vcc, s15, v20
	v_cvt_pk_bf16_f32 v1, v1, v193
	v_fmac_f32_e32 v42, v40, v12
	s_nop 0
	v_addc_co_u32_e32 v45, vcc, 0, v21, vcc
	global_store_short v[44:45], v1, off offset:-4096
	v_cvt_pk_bf16_f32 v1, v42, v193
	s_mov_b32 s15, 0x1bd78000
	global_store_short v[32:33], v1, off offset:2048
	v_fmac_f32_e32 v38, v36, v12
	v_cvt_pk_bf16_f32 v1, v38, v193
	v_fmac_f32_e32 v7, v5, v12
	v_add_co_u32_e32 v6, vcc, s15, v20
	global_store_short v[44:45], v1, off
	v_cvt_pk_bf16_f32 v1, v7, v193
	s_nop 0
	v_addc_co_u32_e32 v7, vcc, 0, v21, vcc
	s_mov_b32 s15, 0x1bd79000
	global_store_short v[44:45], v1, off offset:2048
	v_fma_f32 v1, v31, v8, v35
	v_add_co_u32_e32 v32, vcc, s15, v20
	v_cvt_pk_bf16_f32 v1, v1, v193
	v_fmac_f32_e32 v11, v9, v8
	s_nop 0
	v_addc_co_u32_e32 v33, vcc, 0, v21, vcc
	global_store_short v[32:33], v1, off offset:-4096
	v_fma_f32 v1, v27, v8, v29
	v_cvt_pk_bf16_f32 v1, v1, v193
	global_store_short v[6:7], v1, off offset:2048
	v_fma_f32 v1, v15, v8, v25
	v_cvt_pk_bf16_f32 v1, v1, v193
	global_store_short v[32:33], v1, off
	v_cvt_pk_bf16_f32 v1, v11, v193
	v_add_co_u32_e32 v6, vcc, 0x1bd7c000, v20
	global_store_short v[32:33], v1, off offset:2048
	v_fmac_f32_e32 v34, v30, v10
	v_cvt_pk_bf16_f32 v1, v34, v193
	v_addc_co_u32_e32 v7, vcc, 0, v21, vcc
	global_store_short v[6:7], v1, off
	v_fmac_f32_e32 v28, v26, v10
	v_cvt_pk_bf16_f32 v1, v28, v193
	global_store_short v[6:7], v1, off offset:2048
	v_add_co_u32_e32 v6, vcc, 0x1bd7d000, v20
	v_fmac_f32_e32 v24, v14, v10
	v_cvt_pk_bf16_f32 v1, v24, v193
	s_nop 0
	v_addc_co_u32_e32 v7, vcc, 0, v21, vcc
	global_store_short v[6:7], v1, off
	v_fmac_f32_e32 v13, v23, v10
	v_cvt_pk_bf16_f32 v1, v13, v193
	s_nop 1
	global_store_short v[6:7], v1, off offset:2048
	s_branch .LBB0_480

; __device__ __forceinline__ float log1p_small(float e) { return e < 0.03f ? e * (1.f - e * (0.5f - e * (0.33333334f - 0.25f * e))) : __logf(1.f + e); }
; template <int DIR>
; __device__ __forceinline__ void lru_item(const Params& p, int item, int lane) {
;     ...
;     const float c8 = -8.f * log1p_small(__expf(-p.lru_lambda[DIR * 1024 + d]));
;     const bf16_t* uu = (const bf16_t*)(p.ws + OFF_U);
;     bf16_t* yl = (bf16_t*)(p.ws + (DIR ? OFF_YLB : OFF_YLF));
;     float hst = 0.f;
;     auto tile_row0 = [&](int t) -> size_t { const bool cx = t < 8; const int tl = cx ? (DIR ? 7 - t : t) : (DIR ? 71 - t : t - 8);
;         return cx ? (size_t)bl * 256 + tl * 32 : (size_t)CGR + (size_t)bl * 2048 + tl * 32; };
;     bf16x8 uf[8], ui0, ui1;
;     { const bf16_t* up = uu + (tile_row0(0) + r) * 1024 + blk * 128 + 8 * h;
; #pragma unroll
;       for (int s = 0; s < 8; ++s) uf[s] = ld8(up + 16 * s);
;       ui0 = ld8(up + 32 * db); ui1 = ld8(up + 32 * db + 16); }
.LBB0_487:
	s_andn2_saveexec_b64 s[4:5], s[8:9]
	v_fmamk_f32 v0, v1, 0xbe800000, v237
	v_fma_f32 v0, -v1, v0, 0.5
	v_fma_f32 v0, -v1, v0, 1.0
	v_mul_f32_e32 v0, v1, v0
	s_or_b64 exec, exec, s[4:5]
	s_ashr_i32 s12, s11, 5
	s_ashr_i32 s13, s12, 31
	s_lshl_b64 s[4:5], s[12:13], 8
	v_mov_b32_e32 v3, s5
	v_or_b32_e32 v2, s4, v160
	v_lshlrev_b64 v[2:3], 11, v[2:3]
	v_lshl_add_u64 v[2:3], s[6:7], 0, v[2:3]
	s_lshl_b32 s8, s10, 1
	s_mov_b32 s9, s67
	v_lshl_add_u64 v[2:3], v[2:3], 0, s[8:9]
	v_lshl_add_u64 v[2:3], v[2:3], 0, v[192:193]
	s_lshl_b32 s100, s101, 16
	v_add_co_u32_e32 v2, vcc, s100, v2
	s_nop 1
	v_addc_co_u32_e32 v3, vcc, 0, v3, vcc
	global_load_dwordx4 v[152:155], v[2:3], off
	global_load_dwordx4 v[148:151], v[2:3], off offset:32
	global_load_dwordx4 v[144:147], v[2:3], off offset:64
	global_load_dwordx4 v[136:139], v[2:3], off offset:96
	global_load_dwordx4 v[132:135], v[2:3], off offset:128
	global_load_dwordx4 v[128:131], v[2:3], off offset:160
	global_load_dwordx4 v[124:127], v[2:3], off offset:192
	global_load_dwordx4 v[120:123], v[2:3], off offset:224
	v_lshl_add_u64 v[2:3], v[2:3], 0, s[66:67]
	global_load_dwordx4 v[156:159], v[2:3], off
	global_load_dwordx4 v[140:143], v[2:3], off offset:32
	v_mul_f32_e32 v0, 0xc1000000, v0
	s_lshl_b64 s[10:11], s[12:13], 22
	v_mul_f32_e32 v174, 0x3fb8aa3b, v0
	v_mov_b32_e32 v1, s11
	v_or_b32_e32 v0, s10, v182
	v_lshl_add_u64 v[172:173], v[164:165], 0, s[8:9]
	v_mov_b32_e32 v169, v168
	v_mov_b32_e32 v171, v170
	v_mov_b32_e32 v175, v174
	s_lshl_b64 s[8:9], s[12:13], 11
	v_lshl_add_u64 v[176:177], v[166:167], 0, v[0:1]
	s_mov_b32 s19, s101
	v_mov_b32_e32 v178, 0
	s_lshl_b32 s10, s101, 16
	s_mov_b32 s11, 0
	s_waitcnt vmcnt(0)
	s_waitcnt lgkmcnt(0)
	s_cmp_eq_u32 s101, 0
	s_cbranch_scc1 .Llru_v2_nob
	s_barrier

; __device__ __forceinline__ f32x16 mfma32(bf16x8 a, bf16x8 b, f32x16 c) { return __builtin_amdgcn_mfma_f32_32x32x16_bf16(a, b, c, 0, 0, 0); }
; template <int DIR>
; __device__ __forceinline__ void lru_item(const Params& p, int item, int lane) {
;     ...
;     for (int t = 0; t < 72; ++t) {
;         const bool is_ctx = t < 8;
;         const int tile = is_ctx ? (DIR ? 7 - t : t) : (DIR ? 71 - t : t - 8);
;         f32x16 Aa, Ai, Au;
; #pragma unroll
;         for (int e = 0; e < 16; ++e) { Aa[e] = 0.f; Ai[e] = 0.f; Au[e] = 0.f; }
; #pragma unroll
;         for (int s = 0; s < 8; ++s) { Aa = mfma32(uf[s], Wa[s], Aa); Ai = mfma32(uf[s], Wi[s], Ai); }
;         Au = mfma32(ui0, I0, Au); Au = mfma32(ui1, I1, Au);
;         { const int tn = t + 1 < 72 ? t + 1 : 71; const bf16_t* up = uu + (tile_row0(tn) + r) * 1024 + blk * 128 + 8 * h;
; #pragma unroll
;           for (int s = 0; s < 8; ++s) uf[s] = ld8(up + 16 * s);
;           ui0 = ld8(up + 32 * db); ui1 = ld8(up + 32 * db + 16); }
.LBB0_490:
	s_add_u32 s10, s10, 0x20000
	v_cndmask_b32_e64 v0, v15, v1, s[2:3]
	v_cndmask_b32_e64 v178, v19, v3, s[2:3]
	s_addc_u32 s11, s11, 0
	v_fmac_f32_e32 v178, v0, v5
	ds_write_b32 v188, v178
	s_waitcnt lgkmcnt(0)
	s_barrier
	s_cmp_ge_u32 s10, 0x480000
	s_mov_b32 s19, s18
	s_cbranch_scc1 .LBB0_473
.LBB0_491:
	v_mfma_f32_32x32x16_bf16 v[32:47], v[152:155], v[56:59], 0
	s_add_i32 s18, s19, 2
	s_min_u32 s12, s18, 0x47
	s_lshl_b32 s20, s12, 5
	s_cmp_gt_u32 s12, 7
	s_mov_b64 s[14:15], -1
	v_mfma_f32_32x32x16_bf16 v[16:31], v[152:155], v[60:63], 0
	v_mfma_f32_32x32x16_bf16 v[32:47], v[148:151], v[64:67], v[32:47]
	v_mfma_f32_32x32x16_bf16 v[16:31], v[148:151], v[68:71], v[16:31]
	v_mfma_f32_32x32x16_bf16 v[32:47], v[144:147], v[72:75], v[32:47]
	v_mfma_f32_32x32x16_bf16 v[16:31], v[144:147], v[76:79], v[16:31]
	v_mfma_f32_32x32x16_bf16 v[32:47], v[136:139], v[80:83], v[32:47]
	v_mfma_f32_32x32x16_bf16 v[16:31], v[136:139], v[84:87], v[16:31]
	v_mfma_f32_32x32x16_bf16 v[32:47], v[132:135], v[88:91], v[32:47]
	v_mfma_f32_32x32x16_bf16 v[16:31], v[132:135], v[92:95], v[16:31]
	v_mfma_f32_32x32x16_bf16 v[32:47], v[128:131], v[96:99], v[32:47]
	v_mfma_f32_32x32x16_bf16 v[16:31], v[128:131], v[100:103], v[16:31]
	v_mfma_f32_32x32x16_bf16 v[32:47], v[124:127], v[104:107], v[32:47]
	v_mfma_f32_32x32x16_bf16 v[16:31], v[124:127], v[108:111], v[16:31]
	v_mfma_f32_32x32x16_bf16 v[0:15], v[156:159], v[48:51], 0
	v_mfma_f32_32x32x16_bf16 v[32:47], v[120:123], v[112:115], v[32:47]
	v_mfma_f32_32x32x16_bf16 v[16:31], v[120:123], v[116:119], v[16:31]
	v_mfma_f32_32x32x16_bf16 v[0:15], v[140:143], v[52:55], v[0:15]
	s_cbranch_scc0 .LBB0_493
	s_add_i32 s12, s20, 0xf00
	s_add_u32 s12, s8, s12
	s_addc_u32 s13, s9, 0
	s_mov_b64 s[14:15], 0

; template <int DIR>
; __device__ __forceinline__ void lru_item(const Params& p, int item, int lane) {
;     ...
;         { const int tn = t + 1 < 72 ? t + 1 : 71; const bf16_t* up = uu + (tile_row0(tn) + r) * 1024 + blk * 128 + 8 * h;
; #pragma unroll
;           for (int s = 0; s < 8; ++s) uf[s] = ld8(up + 16 * s);
;           ui0 = ld8(up + 32 * db); ui1 = ld8(up + 32 * db + 16); }
;         float av[16], bv[16];
; #pragma unroll
;         for (int e = 0; e < 16; e += 2) {
;             const f32x2 xa = (f32x2){Aa[e], Aa[e + 1]} + ba, xi = (f32x2){Ai[e], Ai[e + 1]} + bi, uv = (f32x2){Au[e], Au[e + 1]};
;             const f32x2 ta = xa * -1.4426950408889634f, ti = xi * -1.4426950408889634f;
;             f32x2 da, di; da.x = __builtin_amdgcn_exp2f(ta.x); da.y = __builtin_amdgcn_exp2f(ta.y); di.x = __builtin_amdgcn_exp2f(ti.x); di.y = __builtin_amdgcn_exp2f(ti.y);
;             da = da + 1.f; di = di + 1.f;
;             f32x2 ra, ri; ra.x = __builtin_amdgcn_rcpf(da.x); ra.y = __builtin_amdgcn_rcpf(da.y); ri.x = __builtin_amdgcn_rcpf(di.x); ri.y = __builtin_amdgcn_rcpf(di.y);
;             const f32x2 la = ra * (c8 * 1.4426950408889634f);
;             f32x2 a; a.x = __builtin_amdgcn_exp2f(la.x); a.y = __builtin_amdgcn_exp2f(la.y);
;             f32x2 om = 1.f - a * a; om.x = fmaxf(om.x, 0.f); om.y = fmaxf(om.y, 0.f);
;             f32x2 sq; sq.x = __builtin_amdgcn_sqrtf(om.x); sq.y = __builtin_amdgcn_sqrtf(om.y);
;             const f32x2 b = sq * (ri * uv);
;             const int k0 = DIR ? 15 - e : e, k1 = DIR ? 14 - e : e + 1;
;             av[k0] = a.x; bv[k0] = b.x; av[k1] = a.y; bv[k1] = b.y;
;         }
.LBB0_495:
	s_nop 6
	v_pk_add_f32 v[32:33], v[168:169], v[32:33]
	v_pk_add_f32 v[16:17], v[170:171], v[16:17]
	v_pk_mul_f32 v[32:33], v[32:33], s[90:91] op_sel_hi:[1,0]
	v_pk_mul_f32 v[16:17], v[16:17], s[90:91] op_sel_hi:[1,0]
	v_exp_f32_e32 v32, v32
	v_exp_f32_e32 v33, v33
	v_exp_f32_e32 v182, v16
	v_exp_f32_e32 v183, v17
	v_pk_add_f32 v[34:35], v[168:169], v[34:35]
	v_pk_add_f32 v[32:33], v[32:33], 1.0 op_sel_hi:[1,0]
	v_pk_mul_f32 v[34:35], v[34:35], s[90:91] op_sel_hi:[1,0]
	v_rcp_f32_e32 v32, v32
	v_rcp_f32_e32 v33, v33
	v_exp_f32_e32 v34, v34
	v_exp_f32_e32 v35, v35
	v_pk_add_f32 v[18:19], v[170:171], v[18:19]
	v_pk_mul_f32 v[16:17], v[174:175], v[32:33]
	v_pk_add_f32 v[32:33], v[182:183], 1.0 op_sel_hi:[1,0]
	v_pk_mul_f32 v[18:19], v[18:19], s[90:91] op_sel_hi:[1,0]
	v_rcp_f32_e32 v32, v32
	v_rcp_f32_e32 v33, v33
	v_pk_add_f32 v[36:37], v[168:169], v[36:37]
	v_lshl_add_u64 v[120:121], s[12:13], 0, v[160:161]
	v_pk_mul_f32 v[36:37], v[36:37], s[90:91] op_sel_hi:[1,0]
	v_pk_mul_f32 v[0:1], v[0:1], v[32:33]
	v_pk_add_f32 v[32:33], v[34:35], 1.0 op_sel_hi:[1,0]
	v_exp_f32_e32 v34, v18
	v_rcp_f32_e32 v32, v32
	v_rcp_f32_e32 v33, v33
	v_exp_f32_e32 v35, v19
	v_exp_f32_e32 v36, v36
	v_exp_f32_e32 v37, v37
	v_pk_mul_f32 v[18:19], v[174:175], v[32:33]
	v_pk_add_f32 v[32:33], v[34:35], 1.0 op_sel_hi:[1,0]
	v_exp_f32_e32 v18, v18
	v_exp_f32_e32 v19, v19
	v_rcp_f32_e32 v32, v32
	v_rcp_f32_e32 v33, v33
	v_lshlrev_b64 v[120:121], 11, v[120:121]
	v_pk_fma_f32 v[34:35], v[18:19], v[18:19], 1.0 op_sel_hi:[1,1,0] neg_lo:[1,0,0] neg_hi:[1,0,0]
	v_lshl_add_u64 v[140:141], v[172:173], 0, v[120:121]
	v_max_f32_e32 v34, 0, v34
	v_max_f32_e32 v35, 0, v35
	v_sqrt_f32_e32 v34, v34
	v_sqrt_f32_e32 v35, v35
	v_pk_mul_f32 v[2:3], v[2:3], v[32:33]
	global_load_dwordx4 v[152:155], v[140:141], off
	global_load_dwordx4 v[148:151], v[140:141], off offset:32
	global_load_dwordx4 v[144:147], v[140:141], off offset:64
	global_load_dwordx4 v[136:139], v[140:141], off offset:96
	global_load_dwordx4 v[132:135], v[140:141], off offset:128
	global_load_dwordx4 v[128:131], v[140:141], off offset:160
	global_load_dwordx4 v[124:127], v[140:141], off offset:192
	global_load_dwordx4 v[120:123], v[140:141], off offset:224
	v_lshl_add_u64 v[140:141], v[140:141], 0, s[66:67]
	v_pk_mul_f32 v[32:33], v[2:3], v[34:35]
	v_pk_add_f32 v[2:3], v[170:171], v[20:21]
	v_pk_add_f32 v[20:21], v[36:37], 1.0 op_sel_hi:[1,0]
	v_pk_mul_f32 v[2:3], v[2:3], s[90:91] op_sel_hi:[1,0]
	v_rcp_f32_e32 v20, v20
	v_rcp_f32_e32 v21, v21
	v_exp_f32_e32 v34, v2
	v_exp_f32_e32 v35, v3
	v_pk_add_f32 v[36:37], v[168:169], v[38:39]
	v_pk_mul_f32 v[2:3], v[174:175], v[20:21]
	v_pk_mul_f32 v[36:37], v[36:37], s[90:91] op_sel_hi:[1,0]
	v_pk_add_f32 v[20:21], v[34:35], 1.0 op_sel_hi:[1,0]
	v_exp_f32_e32 v36, v36
	v_rcp_f32_e32 v20, v20
	v_rcp_f32_e32 v21, v21
	v_exp_f32_e32 v37, v37
	v_exp_f32_e32 v2, v2
	v_exp_f32_e32 v3, v3
	v_pk_mul_f32 v[4:5], v[4:5], v[20:21]
	v_pk_add_f32 v[20:21], v[170:171], v[22:23]
	v_pk_add_f32 v[22:23], v[36:37], 1.0 op_sel_hi:[1,0]
	v_pk_fma_f32 v[34:35], v[2:3], v[2:3], 1.0 op_sel_hi:[1,1,0] neg_lo:[1,0,0] neg_hi:[1,0,0]
	v_rcp_f32_e32 v22, v22
	v_rcp_f32_e32 v23, v23
	v_max_f32_e32 v34, 0, v34
	v_max_f32_e32 v35, 0, v35
	v_pk_mul_f32 v[20:21], v[20:21], s[90:91] op_sel_hi:[1,0]
	v_pk_mul_f32 v[22:23], v[174:175], v[22:23]
	v_sqrt_f32_e32 v34, v34
	v_sqrt_f32_e32 v35, v35
	v_exp_f32_e32 v20, v20
	v_exp_f32_e32 v21, v21
	v_exp_f32_e32 v22, v22
	v_exp_f32_e32 v23, v23
	global_load_dwordx4 v[156:159], v[140:141], off
	s_nop 0
	global_load_dwordx4 v[140:143], v[140:141], off offset:32
	v_pk_mul_f32 v[4:5], v[4:5], v[34:35]
	v_pk_add_f32 v[20:21], v[20:21], 1.0 op_sel_hi:[1,0]
	v_pk_fma_f32 v[34:35], v[22:23], v[22:23], 1.0 op_sel_hi:[1,1,0] neg_lo:[1,0,0] neg_hi:[1,0,0]
	v_rcp_f32_e32 v20, v20
	v_rcp_f32_e32 v21, v21
	v_max_f32_e32 v34, 0, v34
	v_max_f32_e32 v35, 0, v35
	v_pk_add_f32 v[36:37], v[168:169], v[40:41]
	v_sqrt_f32_e32 v34, v34
	v_sqrt_f32_e32 v35, v35
	v_pk_mul_f32 v[36:37], v[36:37], s[90:91] op_sel_hi:[1,0]
	v_pk_mul_f32 v[6:7], v[6:7], v[20:21]
	v_exp_f32_e32 v36, v36
	v_exp_f32_e32 v37, v37
	v_pk_mul_f32 v[20:21], v[6:7], v[34:35]
	v_pk_add_f32 v[6:7], v[170:171], v[24:25]
	v_pk_add_f32 v[30:31], v[170:171], v[30:31]
	v_pk_add_f32 v[24:25], v[36:37], 1.0 op_sel_hi:[1,0]
	v_pk_mul_f32 v[6:7], v[6:7], s[90:91] op_sel_hi:[1,0]
	v_rcp_f32_e32 v24, v24
	v_rcp_f32_e32 v25, v25
	v_exp_f32_e32 v34, v6
	v_exp_f32_e32 v35, v7
	v_pk_add_f32 v[36:37], v[168:169], v[42:43]
	v_pk_mul_f32 v[6:7], v[174:175], v[24:25]
	v_pk_mul_f32 v[36:37], v[36:37], s[90:91] op_sel_hi:[1,0]
	v_pk_add_f32 v[24:25], v[34:35], 1.0 op_sel_hi:[1,0]
	v_exp_f32_e32 v36, v36
	v_rcp_f32_e32 v24, v24
	v_rcp_f32_e32 v25, v25
	v_exp_f32_e32 v37, v37
	v_exp_f32_e32 v6, v6
	v_exp_f32_e32 v7, v7
	v_pk_mul_f32 v[8:9], v[8:9], v[24:25]
	v_pk_add_f32 v[24:25], v[170:171], v[26:27]
	v_pk_add_f32 v[26:27], v[36:37], 1.0 op_sel_hi:[1,0]
	v_pk_fma_f32 v[34:35], v[6:7], v[6:7], 1.0 op_sel_hi:[1,1,0] neg_lo:[1,0,0] neg_hi:[1,0,0]
	v_rcp_f32_e32 v26, v26
	v_rcp_f32_e32 v27, v27
	v_max_f32_e32 v34, 0, v34
	v_max_f32_e32 v35, 0, v35
	v_sqrt_f32_e32 v34, v34
	v_sqrt_f32_e32 v35, v35
	v_pk_mul_f32 v[24:25], v[24:25], s[90:91] op_sel_hi:[1,0]
	v_pk_mul_f32 v[26:27], v[174:175], v[26:27]
	v_exp_f32_e32 v24, v24
	v_exp_f32_e32 v25, v25
	v_exp_f32_e32 v40, v26
	v_exp_f32_e32 v41, v27
	v_pk_mul_f32 v[8:9], v[8:9], v[34:35]
	v_pk_add_f32 v[34:35], v[168:169], v[44:45]
	v_pk_add_f32 v[24:25], v[24:25], 1.0 op_sel_hi:[1,0]
	v_pk_mul_f32 v[34:35], v[34:35], s[90:91] op_sel_hi:[1,0]
	v_rcp_f32_e32 v24, v24
	v_rcp_f32_e32 v25, v25
; __device__ __forceinline__ float lane_get(float v, int src_lane) { return __int_as_float(__builtin_amdgcn_ds_bpermute(src_lane << 2, __float_as_int(v))); }
; template <int DIR>
; __device__ __forceinline__ void lru_item(const Params& p, int item, int lane) {
;     ...
;         float av[16], bv[16];
; #pragma unroll
;         for (int e = 0; e < 16; e += 2) {
;             const f32x2 xa = (f32x2){Aa[e], Aa[e + 1]} + ba, xi = (f32x2){Ai[e], Ai[e + 1]} + bi, uv = (f32x2){Au[e], Au[e + 1]};
;             const f32x2 ta = xa * -1.4426950408889634f, ti = xi * -1.4426950408889634f;
;             f32x2 da, di; da.x = __builtin_amdgcn_exp2f(ta.x); da.y = __builtin_amdgcn_exp2f(ta.y); di.x = __builtin_amdgcn_exp2f(ti.x); di.y = __builtin_amdgcn_exp2f(ti.y);
;             da = da + 1.f; di = di + 1.f;
;             f32x2 ra, ri; ra.x = __builtin_amdgcn_rcpf(da.x); ra.y = __builtin_amdgcn_rcpf(da.y); ri.x = __builtin_amdgcn_rcpf(di.x); ri.y = __builtin_amdgcn_rcpf(di.y);
;             const f32x2 la = ra * (c8 * 1.4426950408889634f);
;             f32x2 a; a.x = __builtin_amdgcn_exp2f(la.x); a.y = __builtin_amdgcn_exp2f(la.y);
;             f32x2 om = 1.f - a * a; om.x = fmaxf(om.x, 0.f); om.y = fmaxf(om.y, 0.f);
;             f32x2 sq; sq.x = __builtin_amdgcn_sqrtf(om.x); sq.y = __builtin_amdgcn_sqrtf(om.y);
;             const f32x2 b = sq * (ri * uv);
;             const int k0 = DIR ? 15 - e : e, k1 = DIR ? 14 - e : e + 1;
;             av[k0] = a.x; bv[k0] = b.x; av[k1] = a.y; bv[k1] = b.y;
;         }
;         const int hh = DIR ? 1 - h : h;
;         float Ag[4], Bg[4];
; #pragma unroll
;         for (int q = 0; q < 4; q += 2) {
;             f32x2 A = (f32x2){av[4 * q], av[4 * q + 4]}, B = (f32x2){bv[4 * q], bv[4 * q + 4]};
; #pragma unroll
;             for (int k = 1; k < 4; ++k) { const f32x2 ak = (f32x2){av[4 * q + k], av[4 * q + 4 + k]}, bk = (f32x2){bv[4 * q + k], bv[4 * q + 4 + k]};
;                 A = A * ak; B = B * ak + bk; av[4 * q + k] = A.x; av[4 * q + 4 + k] = A.y; bv[4 * q + k] = B.x; bv[4 * q + 4 + k] = B.y; }
;             Ag[q] = A.x; Ag[q + 1] = A.y; Bg[q] = B.x; Bg[q + 1] = B.y;
;         }
;         float Ap[4], Bp[4];
; #pragma unroll
;         for (int q = 0; q < 4; ++q) { Ap[q] = lane_get(Ag[q], lane ^ 32); Bp[q] = lane_get(Bg[q], lane ^ 32); }
	v_exp_f32_e32 v34, v34
	v_exp_f32_e32 v35, v35
	v_pk_fma_f32 v[26:27], v[40:41], v[40:41], 1.0 op_sel_hi:[1,1,0] neg_lo:[1,0,0] neg_hi:[1,0,0]
	v_pk_mul_f32 v[10:11], v[10:11], v[24:25]
	v_max_f32_e32 v26, 0, v26
	v_max_f32_e32 v27, 0, v27
	v_sqrt_f32_e32 v26, v26
	v_sqrt_f32_e32 v27, v27
	v_pk_add_f32 v[24:25], v[34:35], 1.0 op_sel_hi:[1,0]
	v_exp_f32_e32 v16, v16
	v_rcp_f32_e32 v24, v24
	v_rcp_f32_e32 v25, v25
	v_pk_mul_f32 v[42:43], v[10:11], v[26:27]
	v_pk_add_f32 v[10:11], v[170:171], v[28:29]
	v_exp_f32_e32 v17, v17
	v_pk_mul_f32 v[10:11], v[10:11], s[90:91] op_sel_hi:[1,0]
	v_pk_mul_f32 v[30:31], v[30:31], s[90:91] op_sel_hi:[1,0]
	v_exp_f32_e32 v26, v10
	v_exp_f32_e32 v27, v11
	v_pk_mul_f32 v[10:11], v[174:175], v[24:25]
	v_exp_f32_e32 v30, v30
	v_exp_f32_e32 v10, v10
	v_exp_f32_e32 v11, v11
	v_pk_add_f32 v[24:25], v[26:27], 1.0 op_sel_hi:[1,0]
	v_exp_f32_e32 v31, v31
	v_pk_fma_f32 v[182:183], v[16:17], v[16:17], 1.0 op_sel_hi:[1,1,0] neg_lo:[1,0,0] neg_hi:[1,0,0]
	v_pk_fma_f32 v[26:27], v[10:11], v[10:11], 1.0 op_sel_hi:[1,1,0] neg_lo:[1,0,0] neg_hi:[1,0,0]
	v_max_f32_e32 v179, 0, v182
	v_max_f32_e32 v28, 0, v26
	v_max_f32_e32 v29, 0, v27
	v_pk_add_f32 v[26:27], v[168:169], v[46:47]
	v_max_f32_e32 v183, 0, v183
	v_pk_mul_f32 v[26:27], v[26:27], s[90:91] op_sel_hi:[1,0]
	v_sqrt_f32_e32 v182, v179
	v_exp_f32_e32 v26, v26
	v_exp_f32_e32 v27, v27
	v_sqrt_f32_e32 v183, v183
	v_rcp_f32_e32 v24, v24
	v_rcp_f32_e32 v25, v25
	v_pk_add_f32 v[26:27], v[26:27], 1.0 op_sel_hi:[1,0]
	v_sqrt_f32_e32 v28, v28
	v_rcp_f32_e32 v26, v26
	v_rcp_f32_e32 v27, v27
	v_sqrt_f32_e32 v29, v29
	v_pk_mul_f32 v[0:1], v[0:1], v[182:183]
	v_pk_mul_f32 v[12:13], v[12:13], v[24:25]
	v_pk_mul_f32 v[26:27], v[174:175], v[26:27]
	v_mov_b32_e32 v24, v0
	v_exp_f32_e32 v44, v26
	v_exp_f32_e32 v45, v27
	v_pk_add_f32 v[26:27], v[30:31], 1.0 op_sel_hi:[1,0]
	v_mov_b32_e32 v25, v4
	v_rcp_f32_e32 v26, v26
	v_pk_fma_f32 v[30:31], v[44:45], v[44:45], 1.0 op_sel_hi:[1,1,0] neg_lo:[1,0,0] neg_hi:[1,0,0]
	v_rcp_f32_e32 v27, v27
	v_max_f32_e32 v30, 0, v30
	v_max_f32_e32 v31, 0, v31
	v_sqrt_f32_e32 v30, v30
	v_sqrt_f32_e32 v31, v31
	v_pk_mul_f32 v[14:15], v[14:15], v[26:27]
	v_mov_b32_e32 v26, v17
	v_mov_b32_e32 v27, v3
	v_pk_mul_f32 v[46:47], v[14:15], v[30:31]
	v_mov_b32_e32 v14, v16
	v_mov_b32_e32 v15, v2
	v_mov_b32_e32 v30, v1
	v_mov_b32_e32 v31, v5
	v_pk_mul_f32 v[12:13], v[12:13], v[28:29]
	v_pk_mul_f32 v[28:29], v[14:15], v[26:27]
	v_pk_fma_f32 v[30:31], v[26:27], v[24:25], v[30:31]
	v_mov_b32_e32 v14, v18
	v_mov_b32_e32 v15, v22
	v_mov_b32_e32 v24, v32
	v_mov_b32_e32 v25, v20
	v_pk_mul_f32 v[34:35], v[14:15], v[28:29]
	v_pk_fma_f32 v[36:37], v[14:15], v[30:31], v[24:25]
	v_mov_b32_e32 v22, v19
	v_mov_b32_e32 v20, v33
	v_pk_mul_f32 v[32:33], v[22:23], v[34:35]
	v_pk_fma_f32 v[38:39], v[22:23], v[36:37], v[20:21]
	v_mov_b32_e32 v14, v6
	v_mov_b32_e32 v15, v10
	v_mov_b32_e32 v18, v8
	v_mov_b32_e32 v19, v12
	v_mov_b32_e32 v22, v7
	v_mov_b32_e32 v23, v11
	v_mov_b32_e32 v24, v9
	v_mov_b32_e32 v25, v13
	ds_bpermute_b32 v5, v180, v32
	ds_bpermute_b32 v9, v180, v38
	v_pk_mul_f32 v[20:21], v[14:15], v[22:23]
	v_pk_fma_f32 v[22:23], v[22:23], v[18:19], v[24:25]
	v_mov_b32_e32 v14, v40
	v_mov_b32_e32 v15, v44
	v_mov_b32_e32 v18, v42
	v_mov_b32_e32 v19, v46
	v_pk_mul_f32 v[24:25], v[14:15], v[20:21]
	v_pk_fma_f32 v[26:27], v[14:15], v[22:23], v[18:19]
	v_mov_b32_e32 v44, v41
	v_mov_b32_e32 v46, v43
	ds_bpermute_b32 v13, v180, v33
	ds_bpermute_b32 v17, v180, v39
	v_pk_mul_f32 v[14:15], v[44:45], v[24:25]
	v_pk_fma_f32 v[18:19], v[44:45], v[26:27], v[46:47]
	ds_bpermute_b32 v40, v180, v14
	ds_bpermute_b32 v41, v180, v18
	s_waitcnt lgkmcnt(0)
	v_cndmask_b32_e64 v11, v5, v32, s[2:3]
	v_cndmask_b32_e64 v7, v9, v38, s[2:3]
	s_barrier
; __device__ __forceinline__ unsigned short f2bf(float f) { return (unsigned short)(cvt_pk_bf16(f, 0.f) & 0xffffu); }
; template <int DIR>
; __device__ __forceinline__ void lru_item(const Params& p, int item, int lane) {
;     ...
;         float st = hst, hs[4];
; #pragma unroll
;         for (int Gi = 0; Gi < 8; ++Gi) {
;             const int q = Gi >> 1; const bool own = (hh == (Gi & 1));
;             const float A = own ? Ag[q] : Ap[q], B = own ? Bg[q] : Bp[q];
;             if (own) hs[q] = st;
;             st = A * st + B;
;         }
;         hst = st;
;         if (!is_ctx) {
;             bf16_t* yr = yl + ((size_t)bl * 2048 + tile * 32) * 1024 + d;
; #pragma unroll
;             for (int e = 0; e < 16; ++e) { const int k = DIR ? 15 - e : e; const float hv = av[k] * hs[k >> 2] + bv[k];
;                 const int tok = (e & 3) + 8 * (e >> 2) + 4 * h; yr[(size_t)tok * 1024] = f2bf(hv); }
	ds_read_b32 v178, v188
	s_waitcnt lgkmcnt(0)
	ds_bpermute_b32 v1, v180, v15
	ds_bpermute_b32 v3, v180, v19
	v_fmac_f32_e32 v7, v178, v11
	v_cndmask_b32_e64 v5, v32, v5, s[2:3]
	v_cndmask_b32_e64 v9, v38, v9, s[2:3]
	v_fmac_f32_e32 v9, v5, v7
	v_cndmask_b32_e64 v5, v13, v33, s[2:3]
	v_cndmask_b32_e64 v11, v17, v39, s[2:3]
	v_fmac_f32_e32 v11, v5, v9
	v_cndmask_b32_e64 v5, v33, v13, s[2:3]
	v_cndmask_b32_e64 v13, v39, v17, s[2:3]
	v_fmac_f32_e32 v13, v5, v11
	v_cndmask_b32_e64 v5, v40, v14, s[2:3]
	v_cndmask_b32_e64 v17, v41, v18, s[2:3]
	v_fmac_f32_e32 v17, v5, v13
	v_cndmask_b32_e64 v5, v14, v40, s[2:3]
	v_cndmask_b32_e64 v40, v18, v41, s[2:3]
	v_fmac_f32_e32 v40, v5, v17
	s_waitcnt lgkmcnt(1)
	v_cndmask_b32_e64 v41, v1, v15, s[2:3]
	s_waitcnt lgkmcnt(0)
	v_cndmask_b32_e64 v5, v3, v19, s[2:3]
	s_cmp_lt_u32 s19, 8
	v_fmac_f32_e32 v5, v41, v40
	s_waitcnt vmcnt(0)
	s_cbranch_scc1 .LBB0_490
	v_cndmask_b32_e64 v7, v7, v178, s[2:3]
	v_cndmask_b32_e64 v13, v17, v13, s[2:3]
	v_fmac_f32_e32 v0, v16, v7
	v_lshl_add_u64 v[16:17], v[176:177], 0, s[10:11]
	s_mov_b32 s12, 0x17880000
	v_cndmask_b32_e64 v44, v5, v40, s[2:3]
	v_add_co_u32_e32 v40, vcc, s12, v16
	s_mov_b32 s12, 0x17881000
	s_nop 0
	v_addc_co_u32_e32 v41, vcc, 0, v17, vcc
	v_add_co_u32_e32 v42, vcc, s12, v16
	v_cvt_pk_bf16_f32 v0, v0, v193
	s_mov_b32 s12, 0x17884000
	s_nop 0
	v_addc_co_u32_e32 v43, vcc, 0, v17, vcc
	global_store_short v[42:43], v0, off offset:-4096
	v_fma_f32 v0, v28, v7, v30
	v_cvt_pk_bf16_f32 v0, v0, v193
	global_store_short v[40:41], v0, off offset:2048
	v_fma_f32 v0, v34, v7, v36
	v_cvt_pk_bf16_f32 v0, v0, v193
	v_add_co_u32_e32 v40, vcc, s12, v16
	global_store_short v[42:43], v0, off
	v_fma_f32 v0, v32, v7, v38
	v_addc_co_u32_e32 v41, vcc, 0, v17, vcc
	s_mov_b32 s12, 0x17885000
	v_cndmask_b32_e64 v9, v11, v9, s[2:3]
	v_cvt_pk_bf16_f32 v0, v0, v193
	global_store_short v[42:43], v0, off offset:2048
	v_add_co_u32_e32 v42, vcc, s12, v16
	v_fmac_f32_e32 v4, v2, v9
	v_cvt_pk_bf16_f32 v0, v4, v193
	s_nop 0
	v_addc_co_u32_e32 v43, vcc, 0, v17, vcc
	global_store_short v[42:43], v0, off offset:-4096
	v_fmac_f32_e32 v31, v29, v9
	v_cvt_pk_bf16_f32 v0, v31, v193
	s_mov_b32 s12, 0x17888000
	global_store_short v[40:41], v0, off offset:2048
	v_fmac_f32_e32 v37, v35, v9
	v_cvt_pk_bf16_f32 v0, v37, v193
	v_fmac_f32_e32 v8, v6, v13
	v_add_co_u32_e32 v6, vcc, s12, v16
	global_store_short v[42:43], v0, off
	v_fmac_f32_e32 v39, v33, v9
	v_cvt_pk_bf16_f32 v0, v39, v193
	v_addc_co_u32_e32 v7, vcc, 0, v17, vcc
	s_mov_b32 s12, 0x17889000
	global_store_short v[42:43], v0, off offset:2048
	v_cvt_pk_bf16_f32 v0, v8, v193
	v_add_co_u32_e32 v8, vcc, s12, v16
	v_fmac_f32_e32 v12, v10, v44
	s_nop 0
	v_addc_co_u32_e32 v9, vcc, 0, v17, vcc
	global_store_short v[8:9], v0, off offset:-4096
	v_fma_f32 v0, v20, v13, v22
	v_cvt_pk_bf16_f32 v0, v0, v193
	global_store_short v[6:7], v0, off offset:2048
	v_fma_f32 v0, v24, v13, v26
	v_cvt_pk_bf16_f32 v0, v0, v193
	global_store_short v[8:9], v0, off
	v_fma_f32 v0, v14, v13, v18
	v_cvt_pk_bf16_f32 v0, v0, v193
	v_add_co_u32_e32 v6, vcc, 0x1788c000, v16
	global_store_short v[8:9], v0, off offset:2048
	v_cvt_pk_bf16_f32 v0, v12, v193
	s_nop 0
	v_addc_co_u32_e32 v7, vcc, 0, v17, vcc
	global_store_short v[6:7], v0, off
	v_fmac_f32_e32 v23, v21, v44
	v_cvt_pk_bf16_f32 v0, v23, v193
	global_store_short v[6:7], v0, off offset:2048
	v_add_co_u32_e32 v6, vcc, 0x1788d000, v16
	v_fmac_f32_e32 v27, v25, v44
	v_cvt_pk_bf16_f32 v0, v27, v193
	s_nop 0
	v_addc_co_u32_e32 v7, vcc, 0, v17, vcc
	global_store_short v[6:7], v0, off
	v_fma_f32 v0, v15, v44, v19
	v_cvt_pk_bf16_f32 v0, v0, v193
	s_nop 1
	global_store_short v[6:7], v0, off offset:2048
	s_branch .LBB0_490
